# out-GEMM residual epilogue: 12 x-loads in flight over 3 row blocks instead of 32 serialized load-wait-store round trips (plus earlier ph_rec DMA-helper and f3 changes)
# speedup vs baseline: 1.0329x; 1.0156x over previous
.LBB0_365:
	v_lshl_add_u32 v156, s87, 8, v158
	v_lshl_or_b32 v154, s0, 8, v160
	v_ashrrev_i32_e32 v157, 31, v156
	s_lshl_b64 s[6:7], s[28:29], 2
	v_ashrrev_i32_e32 v155, 31, v154
	v_lshlrev_b64 v[152:153], 11, v[156:157]
	s_add_u32 s6, s44, s6
	v_lshl_add_u64 v[152:153], v[152:153], 0, v[154:155]
	s_addc_u32 s7, s45, s7
	v_lshlrev_b64 v[152:153], 2, v[152:153]
	v_lshl_add_u64 v[130:131], v[154:155], 2, s[6:7]
	v_lshl_add_u64 v[166:167], s[26:27], 0, v[152:153]
	global_load_dwordx4 v[142:145], v[130:131], off
	global_load_dwordx4 v[138:141], v[130:131], off offset:64
	global_load_dwordx4 v[134:137], v[130:131], off offset:512
	s_nop 0
	global_load_dwordx4 v[130:133], v[130:131], off offset:576
	s_and_b64 vcc, exec, s[38:39]
	s_mov_b32 s0, s2
	s_mov_b32 s87, s4
	s_mov_b64 s[28:29], s[16:17]
	v_readlane_b32 s94, v254, 63
	s_mov_b32 s25, 0x800000
	v_lshl_add_u64 v[162:163], s[88:89], 0, v[152:153]
	global_load_dwordx4 v[168:171], v[166:167], off
	global_load_dwordx4 v[172:175], v[166:167], off offset:64
	global_load_dwordx4 v[176:179], v[166:167], off offset:512
	global_load_dwordx4 v[180:183], v[166:167], off offset:576
	s_mov_b64 s[6:7], 0x20000
	v_lshl_add_u64 v[224:225], v[166:167], 0, s[6:7]
	global_load_dwordx4 v[184:187], v[224:225], off
	global_load_dwordx4 v[188:191], v[224:225], off offset:64
	global_load_dwordx4 v[192:195], v[224:225], off offset:512
	global_load_dwordx4 v[196:199], v[224:225], off offset:576
	s_mov_b64 s[6:7], 0x40000
	v_lshl_add_u64 v[224:225], v[166:167], 0, s[6:7]
	global_load_dwordx4 v[200:203], v[224:225], off
	global_load_dwordx4 v[212:215], v[224:225], off offset:64
	global_load_dwordx4 v[216:219], v[224:225], off offset:512
	global_load_dwordx4 v[220:223], v[224:225], off offset:576
	s_waitcnt vmcnt(8)
	v_pk_fma_f32 v[126:127], v[126:127], v[144:145], v[170:171]
	v_pk_fma_f32 v[124:125], v[124:125], v[142:143], v[168:169]
	v_pk_fma_f32 v[122:123], v[122:123], v[140:141], v[174:175]
	v_pk_fma_f32 v[120:121], v[120:121], v[138:139], v[172:173]
	v_pk_fma_f32 v[118:119], v[118:119], v[136:137], v[178:179]
	v_pk_fma_f32 v[116:117], v[116:117], v[134:135], v[176:177]
	v_pk_fma_f32 v[114:115], v[114:115], v[132:133], v[182:183]
	v_pk_fma_f32 v[112:113], v[112:113], v[130:131], v[180:181]
	global_store_dwordx4 v[162:163], v[124:127], off
	global_store_dwordx4 v[162:163], v[120:123], off offset:64
	global_store_dwordx4 v[162:163], v[116:119], off offset:512
	global_store_dwordx4 v[162:163], v[112:115], off offset:576
	s_mov_b64 s[6:7], 0x60000
	v_lshl_add_u64 v[224:225], v[166:167], 0, s[6:7]
	global_load_dwordx4 v[168:171], v[224:225], off
	global_load_dwordx4 v[172:175], v[224:225], off offset:64
	global_load_dwordx4 v[176:179], v[224:225], off offset:512
	global_load_dwordx4 v[180:183], v[224:225], off offset:576
	s_waitcnt vmcnt(12)
	s_mov_b64 s[6:7], 0x20000
	v_lshl_add_u64 v[226:227], v[162:163], 0, s[6:7]
	v_pk_fma_f32 v[110:111], v[110:111], v[144:145], v[186:187]
	v_pk_fma_f32 v[108:109], v[108:109], v[142:143], v[184:185]
	v_pk_fma_f32 v[106:107], v[106:107], v[140:141], v[190:191]
	v_pk_fma_f32 v[104:105], v[104:105], v[138:139], v[188:189]
	v_pk_fma_f32 v[102:103], v[102:103], v[136:137], v[194:195]
	v_pk_fma_f32 v[100:101], v[100:101], v[134:135], v[192:193]
	v_pk_fma_f32 v[98:99], v[98:99], v[132:133], v[198:199]
	v_pk_fma_f32 v[96:97], v[96:97], v[130:131], v[196:197]
	global_store_dwordx4 v[226:227], v[108:111], off
	global_store_dwordx4 v[226:227], v[104:107], off offset:64
	global_store_dwordx4 v[226:227], v[100:103], off offset:512
	global_store_dwordx4 v[226:227], v[96:99], off offset:576
	s_mov_b64 s[6:7], 0x100000
	v_lshl_add_u64 v[224:225], v[166:167], 0, s[6:7]
	global_load_dwordx4 v[184:187], v[224:225], off
	global_load_dwordx4 v[188:191], v[224:225], off offset:64
	global_load_dwordx4 v[192:195], v[224:225], off offset:512
	global_load_dwordx4 v[196:199], v[224:225], off offset:576
	s_waitcnt vmcnt(16)
	s_mov_b64 s[6:7], 0x40000
	v_lshl_add_u64 v[226:227], v[162:163], 0, s[6:7]
	v_pk_fma_f32 v[94:95], v[94:95], v[144:145], v[202:203]
	v_pk_fma_f32 v[92:93], v[92:93], v[142:143], v[200:201]
	v_pk_fma_f32 v[90:91], v[90:91], v[140:141], v[214:215]
	v_pk_fma_f32 v[88:89], v[88:89], v[138:139], v[212:213]
	v_pk_fma_f32 v[86:87], v[86:87], v[136:137], v[218:219]
	v_pk_fma_f32 v[84:85], v[84:85], v[134:135], v[216:217]
	v_pk_fma_f32 v[82:83], v[82:83], v[132:133], v[222:223]
	v_pk_fma_f32 v[80:81], v[80:81], v[130:131], v[220:221]
	global_store_dwordx4 v[226:227], v[92:95], off
	global_store_dwordx4 v[226:227], v[88:91], off offset:64
	global_store_dwordx4 v[226:227], v[84:87], off offset:512
	global_store_dwordx4 v[226:227], v[80:83], off offset:576
	s_mov_b64 s[6:7], 0x120000
	v_lshl_add_u64 v[224:225], v[166:167], 0, s[6:7]
	global_load_dwordx4 v[200:203], v[224:225], off
	global_load_dwordx4 v[212:215], v[224:225], off offset:64
	global_load_dwordx4 v[216:219], v[224:225], off offset:512
	global_load_dwordx4 v[220:223], v[224:225], off offset:576
	s_waitcnt vmcnt(16)
	s_mov_b64 s[6:7], 0x60000
	v_lshl_add_u64 v[226:227], v[162:163], 0, s[6:7]
	v_pk_fma_f32 v[78:79], v[78:79], v[144:145], v[170:171]
	v_pk_fma_f32 v[76:77], v[76:77], v[142:143], v[168:169]
	v_pk_fma_f32 v[74:75], v[74:75], v[140:141], v[174:175]
	v_pk_fma_f32 v[72:73], v[72:73], v[138:139], v[172:173]
	v_pk_fma_f32 v[70:71], v[70:71], v[136:137], v[178:179]
	v_pk_fma_f32 v[68:69], v[68:69], v[134:135], v[176:177]
	v_pk_fma_f32 v[66:67], v[66:67], v[132:133], v[182:183]
	v_pk_fma_f32 v[64:65], v[64:65], v[130:131], v[180:181]
	global_store_dwordx4 v[226:227], v[76:79], off
	global_store_dwordx4 v[226:227], v[72:75], off offset:64
	global_store_dwordx4 v[226:227], v[68:71], off offset:512
	global_store_dwordx4 v[226:227], v[64:67], off offset:576
	s_mov_b64 s[6:7], 0x140000
	v_lshl_add_u64 v[224:225], v[166:167], 0, s[6:7]
	global_load_dwordx4 v[168:171], v[224:225], off
	global_load_dwordx4 v[172:175], v[224:225], off offset:64
	global_load_dwordx4 v[176:179], v[224:225], off offset:512
	global_load_dwordx4 v[180:183], v[224:225], off offset:576
	s_waitcnt vmcnt(16)
	s_mov_b64 s[6:7], 0x100000
	v_lshl_add_u64 v[226:227], v[162:163], 0, s[6:7]
	v_pk_fma_f32 v[62:63], v[62:63], v[144:145], v[186:187]
	v_pk_fma_f32 v[60:61], v[60:61], v[142:143], v[184:185]
	v_pk_fma_f32 v[58:59], v[58:59], v[140:141], v[190:191]
	v_pk_fma_f32 v[56:57], v[56:57], v[138:139], v[188:189]
	v_pk_fma_f32 v[54:55], v[54:55], v[136:137], v[194:195]
	v_pk_fma_f32 v[52:53], v[52:53], v[134:135], v[192:193]
	v_pk_fma_f32 v[50:51], v[50:51], v[132:133], v[198:199]
	v_pk_fma_f32 v[48:49], v[48:49], v[130:131], v[196:197]
	global_store_dwordx4 v[226:227], v[60:63], off
	global_store_dwordx4 v[226:227], v[56:59], off offset:64
	global_store_dwordx4 v[226:227], v[52:55], off offset:512
	global_store_dwordx4 v[226:227], v[48:51], off offset:576
	s_mov_b64 s[6:7], 0x160000
	v_lshl_add_u64 v[224:225], v[166:167], 0, s[6:7]
	global_load_dwordx4 v[184:187], v[224:225], off
	global_load_dwordx4 v[188:191], v[224:225], off offset:64
	global_load_dwordx4 v[192:195], v[224:225], off offset:512
	global_load_dwordx4 v[196:199], v[224:225], off offset:576
	s_waitcnt vmcnt(16)
	s_mov_b64 s[6:7], 0x120000
	v_lshl_add_u64 v[226:227], v[162:163], 0, s[6:7]
	v_pk_fma_f32 v[46:47], v[46:47], v[144:145], v[202:203]
	v_pk_fma_f32 v[44:45], v[44:45], v[142:143], v[200:201]
	v_pk_fma_f32 v[42:43], v[42:43], v[140:141], v[214:215]
	v_pk_fma_f32 v[40:41], v[40:41], v[138:139], v[212:213]
	v_pk_fma_f32 v[38:39], v[38:39], v[136:137], v[218:219]
	v_pk_fma_f32 v[36:37], v[36:37], v[134:135], v[216:217]
	v_pk_fma_f32 v[34:35], v[34:35], v[132:133], v[222:223]
	v_pk_fma_f32 v[32:33], v[32:33], v[130:131], v[220:221]
	global_store_dwordx4 v[226:227], v[44:47], off
	global_store_dwordx4 v[226:227], v[40:43], off offset:64
	global_store_dwordx4 v[226:227], v[36:39], off offset:512
	global_store_dwordx4 v[226:227], v[32:35], off offset:576
	s_waitcnt vmcnt(12)
	s_mov_b64 s[6:7], 0x140000
	v_lshl_add_u64 v[226:227], v[162:163], 0, s[6:7]
	v_pk_fma_f32 v[30:31], v[30:31], v[144:145], v[170:171]
	v_pk_fma_f32 v[28:29], v[28:29], v[142:143], v[168:169]
	v_pk_fma_f32 v[26:27], v[26:27], v[140:141], v[174:175]
	v_pk_fma_f32 v[24:25], v[24:25], v[138:139], v[172:173]
	v_pk_fma_f32 v[22:23], v[22:23], v[136:137], v[178:179]
	v_pk_fma_f32 v[20:21], v[20:21], v[134:135], v[176:177]
	v_pk_fma_f32 v[18:19], v[18:19], v[132:133], v[182:183]
	v_pk_fma_f32 v[16:17], v[16:17], v[130:131], v[180:181]
	global_store_dwordx4 v[226:227], v[28:31], off
	global_store_dwordx4 v[226:227], v[24:27], off offset:64
	global_store_dwordx4 v[226:227], v[20:23], off offset:512
	global_store_dwordx4 v[226:227], v[16:19], off offset:576
	s_waitcnt vmcnt(8)
	s_mov_b64 s[6:7], 0x160000
	v_lshl_add_u64 v[226:227], v[162:163], 0, s[6:7]
	v_pk_fma_f32 v[14:15], v[14:15], v[144:145], v[186:187]
	v_pk_fma_f32 v[12:13], v[12:13], v[142:143], v[184:185]
	v_pk_fma_f32 v[10:11], v[10:11], v[140:141], v[190:191]
	v_pk_fma_f32 v[8:9], v[8:9], v[138:139], v[188:189]
	v_pk_fma_f32 v[6:7], v[6:7], v[136:137], v[194:195]
	v_pk_fma_f32 v[4:5], v[4:5], v[134:135], v[192:193]
	v_pk_fma_f32 v[2:3], v[2:3], v[132:133], v[198:199]
	v_pk_fma_f32 v[0:1], v[0:1], v[130:131], v[196:197]
	global_store_dwordx4 v[226:227], v[12:15], off
	global_store_dwordx4 v[226:227], v[8:11], off offset:64
	global_store_dwordx4 v[226:227], v[4:7], off offset:512
	global_store_dwordx4 v[226:227], v[0:3], off offset:576
	s_mov_b64 s[26:27], s[10:11]
	s_cbranch_vccnz .LBB0_372
